# B-out epilogue fused with the final RMSNorm: x1+acc stays in registers across the grid barrier, per-row sums of squares via f32 atomics into the zeroed (unused) SSQ2 array, final output stored once; s
# speedup vs baseline: 1.0147x; 1.0147x over previous
.LBB0_1065:
	s_and_b32 s60, s2, 7
	s_lshr_b32 s61, s2, 3
	s_lshl_b32 s60, s60, 3
	s_lshr_b32 s62, s61, 2
	s_add_i32 s60, s60, s62
	s_and_b32 s61, s61, 3
	s_lshr_b32 s67, s63, 2
	s_and_b32 s68, s63, 3
	s_mul_i32 s69, s60, 0x110
	s_lshl_b32 s70, s67, 6
	s_add_i32 s69, s69, s70
	s_lshl_b32 s70, s61, 8
	s_lshl_b32 s71, s68, 5
	s_add_i32 s70, s70, s71
	v_and_b32_e32 v248, 15, v200
	v_lshrrev_b32_e32 v249, 4, v200
	v_add_u32_e32 v254, s69, v248
	v_lshlrev_b32_e32 v143, 12, v254
	v_lshlrev_b32_e32 v145, 2, v254
	v_lshl_add_u32 v249, v249, 2, s70
	v_lshl_add_u32 v143, v249, 2, v143
	s_sub_u32 s74, s10, 0x33099000
	s_subb_u32 s75, s11, 0
	s_mov_b32 s80, s8
	s_mov_b32 s81, s9
	s_waitcnt lgkmcnt(0)
	v_mov_b32_e32 v254, v143
	global_load_dwordx4 v[210:213], v254, s[10:11]
	global_load_dwordx4 v[214:217], v254, s[10:11] offset:64
	global_load_dwordx4 v[218:221], v254, s[10:11] offset:512
	global_load_dwordx4 v[222:225], v254, s[10:11] offset:576
	v_add_u32_e32 v254, 0x10000, v143
	global_load_dwordx4 v[226:229], v254, s[10:11]
	global_load_dwordx4 v[128:131], v254, s[10:11] offset:64
	global_load_dwordx4 v[132:135], v254, s[10:11] offset:512
	global_load_dwordx4 v[136:139], v254, s[10:11] offset:576
	s_waitcnt vmcnt(7)
	v_pk_add_f32 v[124:125], v[210:211], v[124:125]
	v_pk_add_f32 v[126:127], v[212:213], v[126:127]
	v_add_u32_e32 v254, 0x20000, v143
	global_load_dwordx4 v[210:213], v254, s[10:11]
	v_mul_f32_e32 v248, v124, v124
	v_fmac_f32_e32 v248, v125, v125
	v_mul_f32_e32 v249, v126, v126
	v_fmac_f32_e32 v249, v127, v127
	v_add_f32_e32 v250, v248, v249
	s_waitcnt vmcnt(7)
	v_pk_add_f32 v[120:121], v[214:215], v[120:121]
	v_pk_add_f32 v[122:123], v[216:217], v[122:123]
	global_load_dwordx4 v[214:217], v254, s[10:11] offset:64
	v_mul_f32_e32 v248, v120, v120
	v_fmac_f32_e32 v248, v121, v121
	v_mul_f32_e32 v249, v122, v122
	v_fmac_f32_e32 v249, v123, v123
	v_add_f32_e32 v248, v248, v249
	v_add_f32_e32 v250, v250, v248
	s_waitcnt vmcnt(7)
	v_pk_add_f32 v[116:117], v[218:219], v[116:117]
	v_pk_add_f32 v[118:119], v[220:221], v[118:119]
	global_load_dwordx4 v[218:221], v254, s[10:11] offset:512
	v_mul_f32_e32 v248, v116, v116
	v_fmac_f32_e32 v248, v117, v117
	v_mul_f32_e32 v249, v118, v118
	v_fmac_f32_e32 v249, v119, v119
	v_add_f32_e32 v248, v248, v249
	v_add_f32_e32 v250, v250, v248
	s_waitcnt vmcnt(7)
	v_pk_add_f32 v[108:109], v[222:223], v[108:109]
	v_pk_add_f32 v[110:111], v[224:225], v[110:111]
	global_load_dwordx4 v[222:225], v254, s[10:11] offset:576
	v_mul_f32_e32 v248, v108, v108
	v_fmac_f32_e32 v248, v109, v109
	v_mul_f32_e32 v249, v110, v110
	v_fmac_f32_e32 v249, v111, v111
	v_add_f32_e32 v248, v248, v249
	v_add_f32_e32 v250, v250, v248
	s_waitcnt vmcnt(7)
	v_pk_add_f32 v[112:113], v[226:227], v[112:113]
	v_pk_add_f32 v[114:115], v[228:229], v[114:115]
	v_add_u32_e32 v254, 0x30000, v143
	global_load_dwordx4 v[226:229], v254, s[10:11]
	v_mul_f32_e32 v248, v112, v112
	v_fmac_f32_e32 v248, v113, v113
	v_mul_f32_e32 v249, v114, v114
	v_fmac_f32_e32 v249, v115, v115
	v_add_f32_e32 v251, v248, v249
	s_waitcnt vmcnt(7)
	v_pk_add_f32 v[104:105], v[128:129], v[104:105]
	v_pk_add_f32 v[106:107], v[130:131], v[106:107]
	global_load_dwordx4 v[128:131], v254, s[10:11] offset:64
	v_mul_f32_e32 v248, v104, v104
	v_fmac_f32_e32 v248, v105, v105
	v_mul_f32_e32 v249, v106, v106
	v_fmac_f32_e32 v249, v107, v107
	v_add_f32_e32 v248, v248, v249
	v_add_f32_e32 v251, v251, v248
	s_waitcnt vmcnt(7)
	v_pk_add_f32 v[100:101], v[132:133], v[100:101]
	v_pk_add_f32 v[102:103], v[134:135], v[102:103]
	global_load_dwordx4 v[132:135], v254, s[10:11] offset:512
	v_mul_f32_e32 v248, v100, v100
	v_fmac_f32_e32 v248, v101, v101
	v_mul_f32_e32 v249, v102, v102
	v_fmac_f32_e32 v249, v103, v103
	v_add_f32_e32 v248, v248, v249
	v_add_f32_e32 v251, v251, v248
	s_waitcnt vmcnt(7)
	v_pk_add_f32 v[92:93], v[136:137], v[92:93]
	v_pk_add_f32 v[94:95], v[138:139], v[94:95]
	global_load_dwordx4 v[136:139], v254, s[10:11] offset:576
	v_mul_f32_e32 v248, v92, v92
	v_fmac_f32_e32 v248, v93, v93
	v_mul_f32_e32 v249, v94, v94
	v_fmac_f32_e32 v249, v95, v95
	v_add_f32_e32 v248, v248, v249
	v_add_f32_e32 v251, v251, v248
	s_waitcnt vmcnt(7)
	v_pk_add_f32 v[96:97], v[210:211], v[96:97]
	v_pk_add_f32 v[98:99], v[212:213], v[98:99]
	v_add_u32_e32 v254, 0x80000, v143
	global_load_dwordx4 v[210:213], v254, s[10:11]
	v_mul_f32_e32 v248, v96, v96
	v_fmac_f32_e32 v248, v97, v97
	v_mul_f32_e32 v249, v98, v98
	v_fmac_f32_e32 v249, v99, v99
	v_add_f32_e32 v252, v248, v249
	s_waitcnt vmcnt(7)
	v_pk_add_f32 v[88:89], v[214:215], v[88:89]
	v_pk_add_f32 v[90:91], v[216:217], v[90:91]
	global_load_dwordx4 v[214:217], v254, s[10:11] offset:64
	v_mul_f32_e32 v248, v88, v88
	v_fmac_f32_e32 v248, v89, v89
	v_mul_f32_e32 v249, v90, v90
	v_fmac_f32_e32 v249, v91, v91
	v_add_f32_e32 v248, v248, v249
	v_add_f32_e32 v252, v252, v248
	s_waitcnt vmcnt(7)
	v_pk_add_f32 v[84:85], v[218:219], v[84:85]
	v_pk_add_f32 v[86:87], v[220:221], v[86:87]
	global_load_dwordx4 v[218:221], v254, s[10:11] offset:512
	v_mul_f32_e32 v248, v84, v84
	v_fmac_f32_e32 v248, v85, v85
	v_mul_f32_e32 v249, v86, v86
	v_fmac_f32_e32 v249, v87, v87
	v_add_f32_e32 v248, v248, v249
	v_add_f32_e32 v252, v252, v248
	s_waitcnt vmcnt(7)
	v_pk_add_f32 v[76:77], v[222:223], v[76:77]
	v_pk_add_f32 v[78:79], v[224:225], v[78:79]
	global_load_dwordx4 v[222:225], v254, s[10:11] offset:576
	v_mul_f32_e32 v248, v76, v76
	v_fmac_f32_e32 v248, v77, v77
	v_mul_f32_e32 v249, v78, v78
	v_fmac_f32_e32 v249, v79, v79
	v_add_f32_e32 v248, v248, v249
	v_add_f32_e32 v252, v252, v248
	s_waitcnt vmcnt(7)
	v_pk_add_f32 v[80:81], v[226:227], v[80:81]
	v_pk_add_f32 v[82:83], v[228:229], v[82:83]
	v_add_u32_e32 v254, 0x90000, v143
	global_load_dwordx4 v[226:229], v254, s[10:11]
	v_mul_f32_e32 v248, v80, v80
	v_fmac_f32_e32 v248, v81, v81
	v_mul_f32_e32 v249, v82, v82
	v_fmac_f32_e32 v249, v83, v83
	v_add_f32_e32 v253, v248, v249
	s_waitcnt vmcnt(7)
	v_pk_add_f32 v[72:73], v[128:129], v[72:73]
	v_pk_add_f32 v[74:75], v[130:131], v[74:75]
	global_load_dwordx4 v[128:131], v254, s[10:11] offset:64
	v_mul_f32_e32 v248, v72, v72
	v_fmac_f32_e32 v248, v73, v73
	v_mul_f32_e32 v249, v74, v74
	v_fmac_f32_e32 v249, v75, v75
	v_add_f32_e32 v248, v248, v249
	v_add_f32_e32 v253, v253, v248
	s_waitcnt vmcnt(7)
	v_pk_add_f32 v[68:69], v[132:133], v[68:69]
	v_pk_add_f32 v[70:71], v[134:135], v[70:71]
	global_load_dwordx4 v[132:135], v254, s[10:11] offset:512
	v_mul_f32_e32 v248, v68, v68
	v_fmac_f32_e32 v248, v69, v69
	v_mul_f32_e32 v249, v70, v70
	v_fmac_f32_e32 v249, v71, v71
	v_add_f32_e32 v248, v248, v249
	v_add_f32_e32 v253, v253, v248
	s_waitcnt vmcnt(7)
	v_pk_add_f32 v[64:65], v[136:137], v[64:65]
	v_pk_add_f32 v[66:67], v[138:139], v[66:67]
	global_load_dwordx4 v[136:139], v254, s[10:11] offset:576
	v_mul_f32_e32 v248, v64, v64
	v_fmac_f32_e32 v248, v65, v65
	v_mul_f32_e32 v249, v66, v66
	v_fmac_f32_e32 v249, v67, v67
	v_add_f32_e32 v248, v248, v249
	v_add_f32_e32 v253, v253, v248
	s_waitcnt vmcnt(7)
	v_pk_add_f32 v[60:61], v[210:211], v[60:61]
	v_pk_add_f32 v[62:63], v[212:213], v[62:63]
	v_add_u32_e32 v254, 0xa0000, v143
	global_load_dwordx4 v[210:213], v254, s[10:11]
	v_mul_f32_e32 v248, v60, v60
	v_fmac_f32_e32 v248, v61, v61
	v_mul_f32_e32 v249, v62, v62
	v_fmac_f32_e32 v249, v63, v63
	v_add_f32_e32 v147, v248, v249
	s_waitcnt vmcnt(7)
	v_pk_add_f32 v[56:57], v[214:215], v[56:57]
	v_pk_add_f32 v[58:59], v[216:217], v[58:59]
	global_load_dwordx4 v[214:217], v254, s[10:11] offset:64
	v_mul_f32_e32 v248, v56, v56
	v_fmac_f32_e32 v248, v57, v57
	v_mul_f32_e32 v249, v58, v58
	v_fmac_f32_e32 v249, v59, v59
	v_add_f32_e32 v248, v248, v249
	v_add_f32_e32 v147, v147, v248
	s_waitcnt vmcnt(7)
	v_pk_add_f32 v[52:53], v[218:219], v[52:53]
	v_pk_add_f32 v[54:55], v[220:221], v[54:55]
	global_load_dwordx4 v[218:221], v254, s[10:11] offset:512
	v_mul_f32_e32 v248, v52, v52
	v_fmac_f32_e32 v248, v53, v53
	v_mul_f32_e32 v249, v54, v54
	v_fmac_f32_e32 v249, v55, v55
	v_add_f32_e32 v248, v248, v249
	v_add_f32_e32 v147, v147, v248
	s_waitcnt vmcnt(7)
	v_pk_add_f32 v[192:193], v[222:223], v[44:45]
	v_pk_add_f32 v[194:195], v[224:225], v[46:47]
	global_load_dwordx4 v[222:225], v254, s[10:11] offset:576
	v_mul_f32_e32 v248, v192, v192
	v_fmac_f32_e32 v248, v193, v193
	v_mul_f32_e32 v249, v194, v194
	v_fmac_f32_e32 v249, v195, v195
	v_add_f32_e32 v248, v248, v249
	v_add_f32_e32 v147, v147, v248
	s_waitcnt vmcnt(7)
	v_pk_add_f32 v[196:197], v[226:227], v[48:49]
	v_pk_add_f32 v[198:199], v[228:229], v[50:51]
	v_add_u32_e32 v254, 0xb0000, v143
	global_load_dwordx4 v[226:229], v254, s[10:11]
	v_mul_f32_e32 v248, v196, v196
	v_fmac_f32_e32 v248, v197, v197
	v_mul_f32_e32 v249, v198, v198
	v_fmac_f32_e32 v249, v199, v199
	v_add_f32_e32 v209, v248, v249
	s_waitcnt vmcnt(7)
	v_pk_add_f32 v[188:189], v[128:129], v[40:41]
	v_pk_add_f32 v[190:191], v[130:131], v[42:43]
	global_load_dwordx4 v[128:131], v254, s[10:11] offset:64
	v_mul_f32_e32 v248, v188, v188
	v_fmac_f32_e32 v248, v189, v189
	v_mul_f32_e32 v249, v190, v190
	v_fmac_f32_e32 v249, v191, v191
	v_add_f32_e32 v248, v248, v249
	v_add_f32_e32 v209, v209, v248
	s_waitcnt vmcnt(7)
	v_pk_add_f32 v[184:185], v[132:133], v[36:37]
	v_pk_add_f32 v[186:187], v[134:135], v[38:39]
	global_load_dwordx4 v[132:135], v254, s[10:11] offset:512
	v_mul_f32_e32 v248, v184, v184
	v_fmac_f32_e32 v248, v185, v185
	v_mul_f32_e32 v249, v186, v186
	v_fmac_f32_e32 v249, v187, v187
	v_add_f32_e32 v248, v248, v249
	v_add_f32_e32 v209, v209, v248
	s_waitcnt vmcnt(7)
	v_pk_add_f32 v[176:177], v[136:137], v[28:29]
	v_pk_add_f32 v[178:179], v[138:139], v[30:31]
	global_load_dwordx4 v[136:139], v254, s[10:11] offset:576
	v_mul_f32_e32 v248, v176, v176
	v_fmac_f32_e32 v248, v177, v177
	v_mul_f32_e32 v249, v178, v178
	v_fmac_f32_e32 v249, v179, v179
	v_add_f32_e32 v248, v248, v249
	v_add_f32_e32 v209, v209, v248
	s_waitcnt vmcnt(7)
	v_pk_add_f32 v[180:181], v[210:211], v[32:33]
	v_pk_add_f32 v[182:183], v[212:213], v[34:35]
	v_mul_f32_e32 v248, v180, v180
	v_fmac_f32_e32 v248, v181, v181
	v_mul_f32_e32 v249, v182, v182
	v_fmac_f32_e32 v249, v183, v183
	v_add_f32_e32 v246, v248, v249
	s_waitcnt vmcnt(6)
	v_pk_add_f32 v[172:173], v[214:215], v[24:25]
	v_pk_add_f32 v[174:175], v[216:217], v[26:27]
	v_mul_f32_e32 v248, v172, v172
	v_fmac_f32_e32 v248, v173, v173
	v_mul_f32_e32 v249, v174, v174
	v_fmac_f32_e32 v249, v175, v175
	v_add_f32_e32 v248, v248, v249
	v_add_f32_e32 v246, v246, v248
	s_waitcnt vmcnt(5)
	v_pk_add_f32 v[168:169], v[218:219], v[20:21]
	v_pk_add_f32 v[170:171], v[220:221], v[22:23]
	v_mul_f32_e32 v248, v168, v168
	v_fmac_f32_e32 v248, v169, v169
	v_mul_f32_e32 v249, v170, v170
	v_fmac_f32_e32 v249, v171, v171
	v_add_f32_e32 v248, v248, v249
	v_add_f32_e32 v246, v246, v248
	s_waitcnt vmcnt(4)
	v_pk_add_f32 v[160:161], v[222:223], v[12:13]
	v_pk_add_f32 v[162:163], v[224:225], v[14:15]
	v_mul_f32_e32 v248, v160, v160
	v_fmac_f32_e32 v248, v161, v161
	v_mul_f32_e32 v249, v162, v162
	v_fmac_f32_e32 v249, v163, v163
	v_add_f32_e32 v248, v248, v249
	v_add_f32_e32 v246, v246, v248
	s_waitcnt vmcnt(3)
	v_pk_add_f32 v[164:165], v[226:227], v[16:17]
	v_pk_add_f32 v[166:167], v[228:229], v[18:19]
	v_mul_f32_e32 v248, v164, v164
	v_fmac_f32_e32 v248, v165, v165
	v_mul_f32_e32 v249, v166, v166
	v_fmac_f32_e32 v249, v167, v167
	v_add_f32_e32 v247, v248, v249
	s_waitcnt vmcnt(2)
	v_pk_add_f32 v[156:157], v[128:129], v[8:9]
	v_pk_add_f32 v[158:159], v[130:131], v[10:11]
	v_mul_f32_e32 v248, v156, v156
	v_fmac_f32_e32 v248, v157, v157
	v_mul_f32_e32 v249, v158, v158
	v_fmac_f32_e32 v249, v159, v159
	v_add_f32_e32 v248, v248, v249
	v_add_f32_e32 v247, v247, v248
	s_waitcnt vmcnt(1)
	v_pk_add_f32 v[152:153], v[132:133], v[4:5]
	v_pk_add_f32 v[154:155], v[134:135], v[6:7]
	v_mul_f32_e32 v248, v152, v152
	v_fmac_f32_e32 v248, v153, v153
	v_mul_f32_e32 v249, v154, v154
	v_fmac_f32_e32 v249, v155, v155
	v_add_f32_e32 v248, v248, v249
	v_add_f32_e32 v247, v247, v248
	s_waitcnt vmcnt(0)
	v_pk_add_f32 v[148:149], v[136:137], v[0:1]
	v_pk_add_f32 v[150:151], v[138:139], v[2:3]
	v_mul_f32_e32 v248, v148, v148
	v_fmac_f32_e32 v248, v149, v149
	v_mul_f32_e32 v249, v150, v150
	v_fmac_f32_e32 v249, v151, v151
	v_add_f32_e32 v248, v248, v249
	v_add_f32_e32 v247, v247, v248
	v_xor_b32_e32 v248, 16, v200
	v_lshlrev_b32_e32 v248, 2, v248
	v_xor_b32_e32 v249, 32, v200
	v_lshlrev_b32_e32 v249, 2, v249
	ds_bpermute_b32 v210, v248, v250
	ds_bpermute_b32 v214, v248, v251
	ds_bpermute_b32 v218, v248, v252
	ds_bpermute_b32 v222, v248, v253
	ds_bpermute_b32 v226, v248, v147
	ds_bpermute_b32 v128, v248, v209
	ds_bpermute_b32 v132, v248, v246
	ds_bpermute_b32 v136, v248, v247
	s_waitcnt lgkmcnt(0)
	v_add_f32_e32 v250, v250, v210
	v_add_f32_e32 v251, v251, v214
	v_add_f32_e32 v252, v252, v218
	v_add_f32_e32 v253, v253, v222
	v_add_f32_e32 v147, v147, v226
	v_add_f32_e32 v209, v209, v128
	v_add_f32_e32 v246, v246, v132
	v_add_f32_e32 v247, v247, v136
	ds_bpermute_b32 v210, v249, v250
	ds_bpermute_b32 v214, v249, v251
	ds_bpermute_b32 v218, v249, v252
	ds_bpermute_b32 v222, v249, v253
	ds_bpermute_b32 v226, v249, v147
	ds_bpermute_b32 v128, v249, v209
	ds_bpermute_b32 v132, v249, v246
	ds_bpermute_b32 v136, v249, v247
	s_waitcnt lgkmcnt(0)
	v_add_f32_e32 v250, v250, v210
	v_add_f32_e32 v251, v251, v214
	v_add_f32_e32 v252, v252, v218
	v_add_f32_e32 v253, v253, v222
	v_add_f32_e32 v147, v147, v226
	v_add_f32_e32 v209, v209, v128
	v_add_f32_e32 v246, v246, v132
	v_add_f32_e32 v247, v247, v136
	s_mov_b32 exec_lo, 0xffff
	s_mov_b32 exec_hi, 0
	v_mov_b32_e32 v254, v145
	global_atomic_add_f32 v254, v250, s[74:75]
	v_add_u32_e32 v254, 0x40, v145
	global_atomic_add_f32 v254, v251, s[74:75]
	v_add_u32_e32 v254, 0x80, v145
	global_atomic_add_f32 v254, v252, s[74:75]
	v_add_u32_e32 v254, 0xc0, v145
	global_atomic_add_f32 v254, v253, s[74:75]
	v_add_u32_e32 v254, 0x200, v145
	global_atomic_add_f32 v254, v147, s[74:75]
	v_add_u32_e32 v254, 0x240, v145
	global_atomic_add_f32 v254, v209, s[74:75]
	v_add_u32_e32 v254, 0x280, v145
	global_atomic_add_f32 v254, v246, s[74:75]
	v_add_u32_e32 v254, 0x2c0, v145
	global_atomic_add_f32 v254, v247, s[74:75]
	s_mov_b64 exec, -1
	s_andn2_b64 vcc, exec, s[4:5]
	s_mov_b64 s[4:5], -1
	s_cbranch_vccnz .LBB0_1058
	s_andn2_b64 vcc, exec, s[6:7]
	s_cbranch_vccnz .LBB0_1057
	s_barrier
	s_branch .LBB0_1057
.LBB0_1068:
	s_mul_i32 s86, s60, 0x110
	s_addk_i32 s86, 0x100
	s_lshl_b32 s87, s67, 7
	s_add_i32 s87, s87, s70
	v_and_b32_e32 v248, 15, v200
	v_lshrrev_b32_e32 v249, 4, v200
	v_add_u32_e32 v248, s86, v248
	v_lshl_add_u32 v249, v249, 2, s87
	v_lshlrev_b32_e32 v254, 12, v248
	v_lshl_add_u32 v254, v249, 2, v254
	global_load_dwordx4 v[210:213], v254, s[10:11]
	global_load_dwordx4 v[214:217], v254, s[10:11] offset:64
	s_cmp_eq_u32 s67, 0
	s_cbranch_scc1 .Lslab9_wr0
	v_mov_b32_e32 v230, v238
	v_mov_b32_e32 v231, v239
	v_mov_b32_e32 v232, v240
	v_mov_b32_e32 v233, v241
	v_mov_b32_e32 v234, v242
	v_mov_b32_e32 v235, v243
	v_mov_b32_e32 v236, v244
	v_mov_b32_e32 v237, v245
.Lslab9_wr0:
	s_waitcnt vmcnt(0)
	v_pk_add_f32 v[230:231], v[210:211], v[230:231]
	v_pk_add_f32 v[232:233], v[212:213], v[232:233]
	v_pk_add_f32 v[234:235], v[214:215], v[234:235]
	v_pk_add_f32 v[236:237], v[216:217], v[236:237]
	v_mul_f32_e32 v250, v230, v230
	v_fmac_f32_e32 v250, v231, v231
	v_fmac_f32_e32 v250, v232, v232
	v_fmac_f32_e32 v250, v233, v233
	v_fmac_f32_e32 v250, v234, v234
	v_fmac_f32_e32 v250, v235, v235
	v_fmac_f32_e32 v250, v236, v236
	v_fmac_f32_e32 v250, v237, v237
	v_xor_b32_e32 v249, 16, v200
	v_lshlrev_b32_e32 v249, 2, v249
	ds_bpermute_b32 v251, v249, v250
	v_xor_b32_e32 v249, 32, v200
	v_lshlrev_b32_e32 v249, 2, v249
	s_waitcnt lgkmcnt(0)
	v_add_f32_e32 v250, v250, v251
	ds_bpermute_b32 v251, v249, v250
	s_waitcnt lgkmcnt(0)
	v_add_f32_e32 v250, v250, v251
	v_lshlrev_b32_e32 v248, 2, v248
	s_mov_b32 exec_lo, 0xffff
	s_mov_b32 exec_hi, 0
	global_atomic_add_f32 v248, v250, s[74:75]
	s_mov_b64 exec, -1
	s_waitcnt vmcnt(0)
	s_barrier

.LBB0_1113:
	s_or_b64 exec, exec, s[34:35]
	v_mov_b32_e32 v0, v201
	s_waitcnt lgkmcnt(0)
	s_barrier
	s_load_dwordx2 s[84:85], s[96:97], 0x40
	v_lshrrev_b32_e32 v46, 4, v200
	v_lshl_add_u32 v46, v46, 2, s70
	v_lshlrev_b32_e32 v46, 2, v46
	s_lshl_b32 s88, s67, 9
	v_add_u32_e32 v45, s88, v46
	v_and_b32_e32 v43, 15, v200
	v_add_u32_e32 v43, s86, v43
	v_lshlrev_b32_e32 v44, 2, v43
	v_lshlrev_b32_e32 v43, 12, v43
	v_add_u32_e32 v43, v43, v45
	s_mov_b32 s89, 0x3a800000
	v_mov_b32_e32 v41, 0x358637bd
	s_waitcnt lgkmcnt(0)
	global_load_dwordx4 v[0:3], v46, s[84:85]
	global_load_dwordx4 v[4:7], v46, s[84:85] offset:64
	global_load_dwordx4 v[8:11], v46, s[84:85] offset:512
	global_load_dwordx4 v[12:15], v46, s[84:85] offset:576
	global_load_dwordx4 v[16:19], v45, s[84:85]
	global_load_dwordx4 v[20:23], v45, s[84:85] offset:64
	v_mov_b32_e32 v42, v145
	global_load_dword v24, v42, s[74:75]
	v_add_u32_e32 v42, 0x40, v145
	global_load_dword v26, v42, s[74:75]
	v_add_u32_e32 v42, 0x80, v145
	global_load_dword v28, v42, s[74:75]
	v_add_u32_e32 v42, 0xc0, v145
	global_load_dword v30, v42, s[74:75]
	v_add_u32_e32 v42, 0x200, v145
	global_load_dword v32, v42, s[74:75]
	v_add_u32_e32 v42, 0x240, v145
	global_load_dword v34, v42, s[74:75]
	v_add_u32_e32 v42, 0x280, v145
	global_load_dword v36, v42, s[74:75]
	v_add_u32_e32 v42, 0x2c0, v145
	global_load_dword v38, v42, s[74:75]
	global_load_dword v40, v44, s[74:75]
	s_waitcnt vmcnt(0)
	v_fma_f32 v24, v24, s89, v41
	v_fma_f32 v26, v26, s89, v41
	v_fma_f32 v28, v28, s89, v41
	v_fma_f32 v30, v30, s89, v41
	v_fma_f32 v32, v32, s89, v41
	v_fma_f32 v34, v34, s89, v41
	v_fma_f32 v36, v36, s89, v41
	v_fma_f32 v38, v38, s89, v41
	v_fma_f32 v40, v40, s89, v41
	v_rsq_f32_e32 v24, v24
	v_rsq_f32_e32 v26, v26
	v_rsq_f32_e32 v28, v28
	v_rsq_f32_e32 v30, v30
	v_rsq_f32_e32 v32, v32
	v_rsq_f32_e32 v34, v34
	v_rsq_f32_e32 v36, v36
	v_rsq_f32_e32 v38, v38
	v_rsq_f32_e32 v40, v40
	s_nop 1
	v_mov_b32_e32 v42, v143
	v_pk_mul_f32 v[124:125], v[124:125], v[24:25] op_sel_hi:[1,0]
	v_pk_mul_f32 v[126:127], v[126:127], v[24:25] op_sel_hi:[1,0]
	v_pk_mul_f32 v[124:125], v[0:1], v[124:125]
	v_pk_mul_f32 v[126:127], v[2:3], v[126:127]
	global_store_dwordx4 v42, v[124:127], s[80:81]
	v_pk_mul_f32 v[120:121], v[120:121], v[24:25] op_sel_hi:[1,0]
	v_pk_mul_f32 v[122:123], v[122:123], v[24:25] op_sel_hi:[1,0]
	v_pk_mul_f32 v[120:121], v[4:5], v[120:121]
	v_pk_mul_f32 v[122:123], v[6:7], v[122:123]
	global_store_dwordx4 v42, v[120:123], s[80:81] offset:64
	v_pk_mul_f32 v[116:117], v[116:117], v[24:25] op_sel_hi:[1,0]
	v_pk_mul_f32 v[118:119], v[118:119], v[24:25] op_sel_hi:[1,0]
	v_pk_mul_f32 v[116:117], v[8:9], v[116:117]
	v_pk_mul_f32 v[118:119], v[10:11], v[118:119]
	global_store_dwordx4 v42, v[116:119], s[80:81] offset:512
	v_pk_mul_f32 v[108:109], v[108:109], v[24:25] op_sel_hi:[1,0]
	v_pk_mul_f32 v[110:111], v[110:111], v[24:25] op_sel_hi:[1,0]
	v_pk_mul_f32 v[108:109], v[12:13], v[108:109]
	v_pk_mul_f32 v[110:111], v[14:15], v[110:111]
	global_store_dwordx4 v42, v[108:111], s[80:81] offset:576
	v_add_u32_e32 v42, 0x10000, v143
	v_pk_mul_f32 v[112:113], v[112:113], v[26:27] op_sel_hi:[1,0]
	v_pk_mul_f32 v[114:115], v[114:115], v[26:27] op_sel_hi:[1,0]
	v_pk_mul_f32 v[112:113], v[0:1], v[112:113]
	v_pk_mul_f32 v[114:115], v[2:3], v[114:115]
	global_store_dwordx4 v42, v[112:115], s[80:81]
	v_pk_mul_f32 v[104:105], v[104:105], v[26:27] op_sel_hi:[1,0]
	v_pk_mul_f32 v[106:107], v[106:107], v[26:27] op_sel_hi:[1,0]
	v_pk_mul_f32 v[104:105], v[4:5], v[104:105]
	v_pk_mul_f32 v[106:107], v[6:7], v[106:107]
	global_store_dwordx4 v42, v[104:107], s[80:81] offset:64
	v_pk_mul_f32 v[100:101], v[100:101], v[26:27] op_sel_hi:[1,0]
	v_pk_mul_f32 v[102:103], v[102:103], v[26:27] op_sel_hi:[1,0]
	v_pk_mul_f32 v[100:101], v[8:9], v[100:101]
	v_pk_mul_f32 v[102:103], v[10:11], v[102:103]
	global_store_dwordx4 v42, v[100:103], s[80:81] offset:512
	v_pk_mul_f32 v[92:93], v[92:93], v[26:27] op_sel_hi:[1,0]
	v_pk_mul_f32 v[94:95], v[94:95], v[26:27] op_sel_hi:[1,0]
	v_pk_mul_f32 v[92:93], v[12:13], v[92:93]
	v_pk_mul_f32 v[94:95], v[14:15], v[94:95]
	global_store_dwordx4 v42, v[92:95], s[80:81] offset:576
	v_add_u32_e32 v42, 0x20000, v143
	v_pk_mul_f32 v[96:97], v[96:97], v[28:29] op_sel_hi:[1,0]
	v_pk_mul_f32 v[98:99], v[98:99], v[28:29] op_sel_hi:[1,0]
	v_pk_mul_f32 v[96:97], v[0:1], v[96:97]
	v_pk_mul_f32 v[98:99], v[2:3], v[98:99]
	global_store_dwordx4 v42, v[96:99], s[80:81]
	v_pk_mul_f32 v[88:89], v[88:89], v[28:29] op_sel_hi:[1,0]
	v_pk_mul_f32 v[90:91], v[90:91], v[28:29] op_sel_hi:[1,0]
	v_pk_mul_f32 v[88:89], v[4:5], v[88:89]
	v_pk_mul_f32 v[90:91], v[6:7], v[90:91]
	global_store_dwordx4 v42, v[88:91], s[80:81] offset:64
	v_pk_mul_f32 v[84:85], v[84:85], v[28:29] op_sel_hi:[1,0]
	v_pk_mul_f32 v[86:87], v[86:87], v[28:29] op_sel_hi:[1,0]
	v_pk_mul_f32 v[84:85], v[8:9], v[84:85]
	v_pk_mul_f32 v[86:87], v[10:11], v[86:87]
	global_store_dwordx4 v42, v[84:87], s[80:81] offset:512
	v_pk_mul_f32 v[76:77], v[76:77], v[28:29] op_sel_hi:[1,0]
	v_pk_mul_f32 v[78:79], v[78:79], v[28:29] op_sel_hi:[1,0]
	v_pk_mul_f32 v[76:77], v[12:13], v[76:77]
	v_pk_mul_f32 v[78:79], v[14:15], v[78:79]
	global_store_dwordx4 v42, v[76:79], s[80:81] offset:576
	v_add_u32_e32 v42, 0x30000, v143
	v_pk_mul_f32 v[80:81], v[80:81], v[30:31] op_sel_hi:[1,0]
	v_pk_mul_f32 v[82:83], v[82:83], v[30:31] op_sel_hi:[1,0]
	v_pk_mul_f32 v[80:81], v[0:1], v[80:81]
	v_pk_mul_f32 v[82:83], v[2:3], v[82:83]
	global_store_dwordx4 v42, v[80:83], s[80:81]
	v_pk_mul_f32 v[72:73], v[72:73], v[30:31] op_sel_hi:[1,0]
	v_pk_mul_f32 v[74:75], v[74:75], v[30:31] op_sel_hi:[1,0]
	v_pk_mul_f32 v[72:73], v[4:5], v[72:73]
	v_pk_mul_f32 v[74:75], v[6:7], v[74:75]
	global_store_dwordx4 v42, v[72:75], s[80:81] offset:64
	v_pk_mul_f32 v[68:69], v[68:69], v[30:31] op_sel_hi:[1,0]
	v_pk_mul_f32 v[70:71], v[70:71], v[30:31] op_sel_hi:[1,0]
	v_pk_mul_f32 v[68:69], v[8:9], v[68:69]
	v_pk_mul_f32 v[70:71], v[10:11], v[70:71]
	global_store_dwordx4 v42, v[68:71], s[80:81] offset:512
	v_pk_mul_f32 v[64:65], v[64:65], v[30:31] op_sel_hi:[1,0]
	v_pk_mul_f32 v[66:67], v[66:67], v[30:31] op_sel_hi:[1,0]
	v_pk_mul_f32 v[64:65], v[12:13], v[64:65]
	v_pk_mul_f32 v[66:67], v[14:15], v[66:67]
	global_store_dwordx4 v42, v[64:67], s[80:81] offset:576
	v_add_u32_e32 v42, 0x80000, v143
	v_pk_mul_f32 v[60:61], v[60:61], v[32:33] op_sel_hi:[1,0]
	v_pk_mul_f32 v[62:63], v[62:63], v[32:33] op_sel_hi:[1,0]
	v_pk_mul_f32 v[60:61], v[0:1], v[60:61]
	v_pk_mul_f32 v[62:63], v[2:3], v[62:63]
	global_store_dwordx4 v42, v[60:63], s[80:81]
	v_pk_mul_f32 v[56:57], v[56:57], v[32:33] op_sel_hi:[1,0]
	v_pk_mul_f32 v[58:59], v[58:59], v[32:33] op_sel_hi:[1,0]
	v_pk_mul_f32 v[56:57], v[4:5], v[56:57]
	v_pk_mul_f32 v[58:59], v[6:7], v[58:59]
	global_store_dwordx4 v42, v[56:59], s[80:81] offset:64
	v_pk_mul_f32 v[52:53], v[52:53], v[32:33] op_sel_hi:[1,0]
	v_pk_mul_f32 v[54:55], v[54:55], v[32:33] op_sel_hi:[1,0]
	v_pk_mul_f32 v[52:53], v[8:9], v[52:53]
	v_pk_mul_f32 v[54:55], v[10:11], v[54:55]
	global_store_dwordx4 v42, v[52:55], s[80:81] offset:512
	v_pk_mul_f32 v[192:193], v[192:193], v[32:33] op_sel_hi:[1,0]
	v_pk_mul_f32 v[194:195], v[194:195], v[32:33] op_sel_hi:[1,0]
	v_pk_mul_f32 v[192:193], v[12:13], v[192:193]
	v_pk_mul_f32 v[194:195], v[14:15], v[194:195]
	global_store_dwordx4 v42, v[192:195], s[80:81] offset:576
	v_add_u32_e32 v42, 0x90000, v143
	v_pk_mul_f32 v[196:197], v[196:197], v[34:35] op_sel_hi:[1,0]
	v_pk_mul_f32 v[198:199], v[198:199], v[34:35] op_sel_hi:[1,0]
	v_pk_mul_f32 v[196:197], v[0:1], v[196:197]
	v_pk_mul_f32 v[198:199], v[2:3], v[198:199]
	global_store_dwordx4 v42, v[196:199], s[80:81]
	v_pk_mul_f32 v[188:189], v[188:189], v[34:35] op_sel_hi:[1,0]
	v_pk_mul_f32 v[190:191], v[190:191], v[34:35] op_sel_hi:[1,0]
	v_pk_mul_f32 v[188:189], v[4:5], v[188:189]
	v_pk_mul_f32 v[190:191], v[6:7], v[190:191]
	global_store_dwordx4 v42, v[188:191], s[80:81] offset:64
	v_pk_mul_f32 v[184:185], v[184:185], v[34:35] op_sel_hi:[1,0]
	v_pk_mul_f32 v[186:187], v[186:187], v[34:35] op_sel_hi:[1,0]
	v_pk_mul_f32 v[184:185], v[8:9], v[184:185]
	v_pk_mul_f32 v[186:187], v[10:11], v[186:187]
	global_store_dwordx4 v42, v[184:187], s[80:81] offset:512
	v_pk_mul_f32 v[176:177], v[176:177], v[34:35] op_sel_hi:[1,0]
	v_pk_mul_f32 v[178:179], v[178:179], v[34:35] op_sel_hi:[1,0]
	v_pk_mul_f32 v[176:177], v[12:13], v[176:177]
	v_pk_mul_f32 v[178:179], v[14:15], v[178:179]
	global_store_dwordx4 v42, v[176:179], s[80:81] offset:576
	v_add_u32_e32 v42, 0xa0000, v143
	v_pk_mul_f32 v[180:181], v[180:181], v[36:37] op_sel_hi:[1,0]
	v_pk_mul_f32 v[182:183], v[182:183], v[36:37] op_sel_hi:[1,0]
	v_pk_mul_f32 v[180:181], v[0:1], v[180:181]
	v_pk_mul_f32 v[182:183], v[2:3], v[182:183]
	global_store_dwordx4 v42, v[180:183], s[80:81]
	v_pk_mul_f32 v[172:173], v[172:173], v[36:37] op_sel_hi:[1,0]
	v_pk_mul_f32 v[174:175], v[174:175], v[36:37] op_sel_hi:[1,0]
	v_pk_mul_f32 v[172:173], v[4:5], v[172:173]
	v_pk_mul_f32 v[174:175], v[6:7], v[174:175]
	global_store_dwordx4 v42, v[172:175], s[80:81] offset:64
	v_pk_mul_f32 v[168:169], v[168:169], v[36:37] op_sel_hi:[1,0]
	v_pk_mul_f32 v[170:171], v[170:171], v[36:37] op_sel_hi:[1,0]
	v_pk_mul_f32 v[168:169], v[8:9], v[168:169]
	v_pk_mul_f32 v[170:171], v[10:11], v[170:171]
	global_store_dwordx4 v42, v[168:171], s[80:81] offset:512
	v_pk_mul_f32 v[160:161], v[160:161], v[36:37] op_sel_hi:[1,0]
	v_pk_mul_f32 v[162:163], v[162:163], v[36:37] op_sel_hi:[1,0]
	v_pk_mul_f32 v[160:161], v[12:13], v[160:161]
	v_pk_mul_f32 v[162:163], v[14:15], v[162:163]
	global_store_dwordx4 v42, v[160:163], s[80:81] offset:576
	v_add_u32_e32 v42, 0xb0000, v143
	v_pk_mul_f32 v[164:165], v[164:165], v[38:39] op_sel_hi:[1,0]
	v_pk_mul_f32 v[166:167], v[166:167], v[38:39] op_sel_hi:[1,0]
	v_pk_mul_f32 v[164:165], v[0:1], v[164:165]
	v_pk_mul_f32 v[166:167], v[2:3], v[166:167]
	global_store_dwordx4 v42, v[164:167], s[80:81]
	v_pk_mul_f32 v[156:157], v[156:157], v[38:39] op_sel_hi:[1,0]
	v_pk_mul_f32 v[158:159], v[158:159], v[38:39] op_sel_hi:[1,0]
	v_pk_mul_f32 v[156:157], v[4:5], v[156:157]
	v_pk_mul_f32 v[158:159], v[6:7], v[158:159]
	global_store_dwordx4 v42, v[156:159], s[80:81] offset:64
	v_pk_mul_f32 v[152:153], v[152:153], v[38:39] op_sel_hi:[1,0]
	v_pk_mul_f32 v[154:155], v[154:155], v[38:39] op_sel_hi:[1,0]
	v_pk_mul_f32 v[152:153], v[8:9], v[152:153]
	v_pk_mul_f32 v[154:155], v[10:11], v[154:155]
	global_store_dwordx4 v42, v[152:155], s[80:81] offset:512
	v_pk_mul_f32 v[148:149], v[148:149], v[38:39] op_sel_hi:[1,0]
	v_pk_mul_f32 v[150:151], v[150:151], v[38:39] op_sel_hi:[1,0]
	v_pk_mul_f32 v[148:149], v[12:13], v[148:149]
	v_pk_mul_f32 v[150:151], v[14:15], v[150:151]
	global_store_dwordx4 v42, v[148:151], s[80:81] offset:576
	v_pk_mul_f32 v[230:231], v[230:231], v[40:41] op_sel_hi:[1,0]
	v_pk_mul_f32 v[232:233], v[232:233], v[40:41] op_sel_hi:[1,0]
	v_pk_mul_f32 v[230:231], v[16:17], v[230:231]
	v_pk_mul_f32 v[232:233], v[18:19], v[232:233]
	global_store_dwordx4 v43, v[230:233], s[80:81]
	v_pk_mul_f32 v[234:235], v[234:235], v[40:41] op_sel_hi:[1,0]
	v_pk_mul_f32 v[236:237], v[236:237], v[40:41] op_sel_hi:[1,0]
	v_pk_mul_f32 v[234:235], v[20:21], v[234:235]
	v_pk_mul_f32 v[236:237], v[22:23], v[236:237]
	global_store_dwordx4 v43, v[234:237], s[80:81] offset:64
	s_endpgm
	s_endpgm
